# Ph5 epilogue rewritten by hand: loader permutes W_up rows so lanes 16 apart own adjacent columns, v_permlane16_swap pairs them, dword stores (64 B contiguous per 16 lanes) replace the 2-byte stores
# baseline (speedup 1.0000x reference)
.LBB0_482:
	s_ashr_i32 s1, s5, 7
	s_lshl_b32 s7, s1, 8
	v_bfe_u32 v128, v197, 5, 1
	v_lshl_add_u32 v129, v128, 4, s7
	v_add_u32_e32 v129, 0x12000, v129
	ds_read_b128 v[132:135], v129
	ds_read_b128 v[136:139], v129 offset:32
	ds_read_b128 v[140:143], v129 offset:64
	ds_read_b128 v[144:147], v129 offset:96
	ds_read_b128 v[148:151], v129 offset:128
	ds_read_b128 v[152:155], v129 offset:160
	ds_read_b128 v[156:159], v129 offset:192
	ds_read_b128 v[160:163], v129 offset:224
	s_lshl_b32 s7, s0, 13
	s_lshl_b32 s36, s6, 1
	s_add_u32 s7, s7, s36
	s_add_u32 s42, s70, s7
	s_addc_u32 s43, s71, 0
	s_mov_b32 s44, 0x05040100
	s_mov_b32 s45, 0x07060302
	s_lshl_b32 s36, s5, 2
	s_and_b32 s36, s36, 0x100
	v_and_b32_e32 v130, 15, v197
	v_lshlrev_b32_e32 v130, 2, v130
	v_add_u32_e32 v130, s36, v130
	v_bfe_u32 v131, v197, 4, 1
	v_lshlrev_b32_e32 v131, 1, v131
	v_lshl_add_u32 v131, v128, 2, v131
	s_lshl_b32 s37, s1, 6
	v_add_u32_e32 v131, s37, v131
	v_lshl_add_u32 v164, v131, 13, v130
	v_add_u32_e32 v165, 0x2000, v164
	s_waitcnt lgkmcnt(0)
	v_mul_f32_e32 v112, v112, v132
	v_mul_f32_e32 v113, v113, v133
	v_mul_f32_e32 v114, v114, v134
	v_mul_f32_e32 v115, v115, v135
	v_mul_f32_e32 v96, v96, v132
	v_mul_f32_e32 v97, v97, v133
	v_mul_f32_e32 v98, v98, v134
	v_mul_f32_e32 v99, v99, v135
	v_mul_f32_e32 v80, v80, v132
	v_mul_f32_e32 v81, v81, v133
	v_mul_f32_e32 v82, v82, v134
	v_mul_f32_e32 v83, v83, v135
	v_mul_f32_e32 v64, v64, v132
	v_mul_f32_e32 v65, v65, v133
	v_mul_f32_e32 v66, v66, v134
	v_mul_f32_e32 v67, v67, v135
	v_max_f32_e32 v112, 0, v112
	v_max_f32_e32 v113, 0, v113
	v_max_f32_e32 v114, 0, v114
	v_max_f32_e32 v115, 0, v115
	v_max_f32_e32 v96, 0, v96
	v_max_f32_e32 v97, 0, v97
	v_max_f32_e32 v98, 0, v98
	v_max_f32_e32 v99, 0, v99
	v_max_f32_e32 v80, 0, v80
	v_max_f32_e32 v81, 0, v81
	v_max_f32_e32 v82, 0, v82
	v_max_f32_e32 v83, 0, v83
	v_max_f32_e32 v64, 0, v64
	v_max_f32_e32 v65, 0, v65
	v_max_f32_e32 v66, 0, v66
	v_max_f32_e32 v67, 0, v67
	v_mul_f32_e32 v112, v112, v112
	v_mul_f32_e32 v113, v113, v113
	v_mul_f32_e32 v114, v114, v114
	v_mul_f32_e32 v115, v115, v115
	v_mul_f32_e32 v96, v96, v96
	v_mul_f32_e32 v97, v97, v97
	v_mul_f32_e32 v98, v98, v98
	v_mul_f32_e32 v99, v99, v99
	v_mul_f32_e32 v80, v80, v80
	v_mul_f32_e32 v81, v81, v81
	v_mul_f32_e32 v82, v82, v82
	v_mul_f32_e32 v83, v83, v83
	v_mul_f32_e32 v64, v64, v64
	v_mul_f32_e32 v65, v65, v65
	v_mul_f32_e32 v66, v66, v66
	v_mul_f32_e32 v67, v67, v67
	v_cvt_pk_bf16_f32 v112, v112, v113
	v_cvt_pk_bf16_f32 v114, v114, v115
	v_cvt_pk_bf16_f32 v96, v96, v97
	v_cvt_pk_bf16_f32 v98, v98, v99
	v_cvt_pk_bf16_f32 v80, v80, v81
	v_cvt_pk_bf16_f32 v82, v82, v83
	v_cvt_pk_bf16_f32 v64, v64, v65
	v_cvt_pk_bf16_f32 v66, v66, v67
	s_nop 1
	v_permlane16_swap_b32 v112, v114
	v_permlane16_swap_b32 v96, v98
	v_permlane16_swap_b32 v80, v82
	v_permlane16_swap_b32 v64, v66
	s_nop 0
	v_perm_b32 v113, v114, v112, s44
	v_perm_b32 v115, v114, v112, s45
	v_perm_b32 v97, v98, v96, s44
	v_perm_b32 v99, v98, v96, s45
	v_perm_b32 v81, v82, v80, s44
	v_perm_b32 v83, v82, v80, s45
	v_perm_b32 v65, v66, v64, s44
	v_perm_b32 v67, v66, v64, s45
	global_store_dword v164, v113, s[42:43]
	global_store_dword v165, v115, s[42:43]
	global_store_dword v164, v97, s[42:43] offset:64
	global_store_dword v165, v99, s[42:43] offset:64
	global_store_dword v164, v81, s[42:43] offset:128
	global_store_dword v165, v83, s[42:43] offset:128
	global_store_dword v164, v65, s[42:43] offset:192
	global_store_dword v165, v67, s[42:43] offset:192
	v_add_u32_e32 v164, 0x10000, v164
	v_add_u32_e32 v165, 0x10000, v165
	v_mul_f32_e32 v116, v116, v136
	v_mul_f32_e32 v117, v117, v137
	v_mul_f32_e32 v118, v118, v138
	v_mul_f32_e32 v119, v119, v139
	v_mul_f32_e32 v100, v100, v136
	v_mul_f32_e32 v101, v101, v137
	v_mul_f32_e32 v102, v102, v138
	v_mul_f32_e32 v103, v103, v139
	v_mul_f32_e32 v84, v84, v136
	v_mul_f32_e32 v85, v85, v137
	v_mul_f32_e32 v86, v86, v138
	v_mul_f32_e32 v87, v87, v139
	v_mul_f32_e32 v68, v68, v136
	v_mul_f32_e32 v69, v69, v137
	v_mul_f32_e32 v70, v70, v138
	v_mul_f32_e32 v71, v71, v139
	v_max_f32_e32 v116, 0, v116
	v_max_f32_e32 v117, 0, v117
	v_max_f32_e32 v118, 0, v118
	v_max_f32_e32 v119, 0, v119
	v_max_f32_e32 v100, 0, v100
	v_max_f32_e32 v101, 0, v101
	v_max_f32_e32 v102, 0, v102
	v_max_f32_e32 v103, 0, v103
	v_max_f32_e32 v84, 0, v84
	v_max_f32_e32 v85, 0, v85
	v_max_f32_e32 v86, 0, v86
	v_max_f32_e32 v87, 0, v87
	v_max_f32_e32 v68, 0, v68
	v_max_f32_e32 v69, 0, v69
	v_max_f32_e32 v70, 0, v70
	v_max_f32_e32 v71, 0, v71
	v_mul_f32_e32 v116, v116, v116
	v_mul_f32_e32 v117, v117, v117
	v_mul_f32_e32 v118, v118, v118
	v_mul_f32_e32 v119, v119, v119
	v_mul_f32_e32 v100, v100, v100
	v_mul_f32_e32 v101, v101, v101
	v_mul_f32_e32 v102, v102, v102
	v_mul_f32_e32 v103, v103, v103
	v_mul_f32_e32 v84, v84, v84
	v_mul_f32_e32 v85, v85, v85
	v_mul_f32_e32 v86, v86, v86
	v_mul_f32_e32 v87, v87, v87
	v_mul_f32_e32 v68, v68, v68
	v_mul_f32_e32 v69, v69, v69
	v_mul_f32_e32 v70, v70, v70
	v_mul_f32_e32 v71, v71, v71
	v_cvt_pk_bf16_f32 v116, v116, v117
	v_cvt_pk_bf16_f32 v118, v118, v119
	v_cvt_pk_bf16_f32 v100, v100, v101
	v_cvt_pk_bf16_f32 v102, v102, v103
	v_cvt_pk_bf16_f32 v84, v84, v85
	v_cvt_pk_bf16_f32 v86, v86, v87
	v_cvt_pk_bf16_f32 v68, v68, v69
	v_cvt_pk_bf16_f32 v70, v70, v71
	s_nop 1
	v_permlane16_swap_b32 v116, v118
	v_permlane16_swap_b32 v100, v102
	v_permlane16_swap_b32 v84, v86
	v_permlane16_swap_b32 v68, v70
	s_nop 0
	v_perm_b32 v117, v118, v116, s44
	v_perm_b32 v119, v118, v116, s45
	v_perm_b32 v101, v102, v100, s44
	v_perm_b32 v103, v102, v100, s45
	v_perm_b32 v85, v86, v84, s44
	v_perm_b32 v87, v86, v84, s45
	v_perm_b32 v69, v70, v68, s44
	v_perm_b32 v71, v70, v68, s45
	global_store_dword v164, v117, s[42:43]
	global_store_dword v165, v119, s[42:43]
	global_store_dword v164, v101, s[42:43] offset:64
	global_store_dword v165, v103, s[42:43] offset:64
	global_store_dword v164, v85, s[42:43] offset:128
	global_store_dword v165, v87, s[42:43] offset:128
	global_store_dword v164, v69, s[42:43] offset:192
	global_store_dword v165, v71, s[42:43] offset:192
	v_add_u32_e32 v164, 0x10000, v164
	v_add_u32_e32 v165, 0x10000, v165
	v_mul_f32_e32 v120, v120, v140
	v_mul_f32_e32 v121, v121, v141
	v_mul_f32_e32 v122, v122, v142
	v_mul_f32_e32 v123, v123, v143
	v_mul_f32_e32 v104, v104, v140
	v_mul_f32_e32 v105, v105, v141
	v_mul_f32_e32 v106, v106, v142
	v_mul_f32_e32 v107, v107, v143
	v_mul_f32_e32 v88, v88, v140
	v_mul_f32_e32 v89, v89, v141
	v_mul_f32_e32 v90, v90, v142
	v_mul_f32_e32 v91, v91, v143
	v_mul_f32_e32 v72, v72, v140
	v_mul_f32_e32 v73, v73, v141
	v_mul_f32_e32 v74, v74, v142
	v_mul_f32_e32 v75, v75, v143
	v_max_f32_e32 v120, 0, v120
	v_max_f32_e32 v121, 0, v121
	v_max_f32_e32 v122, 0, v122
	v_max_f32_e32 v123, 0, v123
	v_max_f32_e32 v104, 0, v104
	v_max_f32_e32 v105, 0, v105
	v_max_f32_e32 v106, 0, v106
	v_max_f32_e32 v107, 0, v107
	v_max_f32_e32 v88, 0, v88
	v_max_f32_e32 v89, 0, v89
	v_max_f32_e32 v90, 0, v90
	v_max_f32_e32 v91, 0, v91
	v_max_f32_e32 v72, 0, v72
	v_max_f32_e32 v73, 0, v73
	v_max_f32_e32 v74, 0, v74
	v_max_f32_e32 v75, 0, v75
	v_mul_f32_e32 v120, v120, v120
	v_mul_f32_e32 v121, v121, v121
	v_mul_f32_e32 v122, v122, v122
	v_mul_f32_e32 v123, v123, v123
	v_mul_f32_e32 v104, v104, v104
	v_mul_f32_e32 v105, v105, v105
	v_mul_f32_e32 v106, v106, v106
	v_mul_f32_e32 v107, v107, v107
	v_mul_f32_e32 v88, v88, v88
	v_mul_f32_e32 v89, v89, v89
	v_mul_f32_e32 v90, v90, v90
	v_mul_f32_e32 v91, v91, v91
	v_mul_f32_e32 v72, v72, v72
	v_mul_f32_e32 v73, v73, v73
	v_mul_f32_e32 v74, v74, v74
	v_mul_f32_e32 v75, v75, v75
	v_cvt_pk_bf16_f32 v120, v120, v121
	v_cvt_pk_bf16_f32 v122, v122, v123
	v_cvt_pk_bf16_f32 v104, v104, v105
	v_cvt_pk_bf16_f32 v106, v106, v107
	v_cvt_pk_bf16_f32 v88, v88, v89
	v_cvt_pk_bf16_f32 v90, v90, v91
	v_cvt_pk_bf16_f32 v72, v72, v73
	v_cvt_pk_bf16_f32 v74, v74, v75
	s_nop 1
	v_permlane16_swap_b32 v120, v122
	v_permlane16_swap_b32 v104, v106
	v_permlane16_swap_b32 v88, v90
	v_permlane16_swap_b32 v72, v74
	s_nop 0
	v_perm_b32 v121, v122, v120, s44
	v_perm_b32 v123, v122, v120, s45
	v_perm_b32 v105, v106, v104, s44
	v_perm_b32 v107, v106, v104, s45
	v_perm_b32 v89, v90, v88, s44
	v_perm_b32 v91, v90, v88, s45
	v_perm_b32 v73, v74, v72, s44
	v_perm_b32 v75, v74, v72, s45
	global_store_dword v164, v121, s[42:43]
	global_store_dword v165, v123, s[42:43]
	global_store_dword v164, v105, s[42:43] offset:64
	global_store_dword v165, v107, s[42:43] offset:64
	global_store_dword v164, v89, s[42:43] offset:128
	global_store_dword v165, v91, s[42:43] offset:128
	global_store_dword v164, v73, s[42:43] offset:192
	global_store_dword v165, v75, s[42:43] offset:192
	v_add_u32_e32 v164, 0x10000, v164
	v_add_u32_e32 v165, 0x10000, v165
	v_mul_f32_e32 v124, v124, v144
	v_mul_f32_e32 v125, v125, v145
	v_mul_f32_e32 v126, v126, v146
	v_mul_f32_e32 v127, v127, v147
	v_mul_f32_e32 v108, v108, v144
	v_mul_f32_e32 v109, v109, v145
	v_mul_f32_e32 v110, v110, v146
	v_mul_f32_e32 v111, v111, v147
	v_mul_f32_e32 v92, v92, v144
	v_mul_f32_e32 v93, v93, v145
	v_mul_f32_e32 v94, v94, v146
	v_mul_f32_e32 v95, v95, v147
	v_mul_f32_e32 v76, v76, v144
	v_mul_f32_e32 v77, v77, v145
	v_mul_f32_e32 v78, v78, v146
	v_mul_f32_e32 v79, v79, v147
	v_max_f32_e32 v124, 0, v124
	v_max_f32_e32 v125, 0, v125
	v_max_f32_e32 v126, 0, v126
	v_max_f32_e32 v127, 0, v127
	v_max_f32_e32 v108, 0, v108
	v_max_f32_e32 v109, 0, v109
	v_max_f32_e32 v110, 0, v110
	v_max_f32_e32 v111, 0, v111
	v_max_f32_e32 v92, 0, v92
	v_max_f32_e32 v93, 0, v93
	v_max_f32_e32 v94, 0, v94
	v_max_f32_e32 v95, 0, v95
	v_max_f32_e32 v76, 0, v76
	v_max_f32_e32 v77, 0, v77
	v_max_f32_e32 v78, 0, v78
	v_max_f32_e32 v79, 0, v79
	v_mul_f32_e32 v124, v124, v124
	v_mul_f32_e32 v125, v125, v125
	v_mul_f32_e32 v126, v126, v126
	v_mul_f32_e32 v127, v127, v127
	v_mul_f32_e32 v108, v108, v108
	v_mul_f32_e32 v109, v109, v109
	v_mul_f32_e32 v110, v110, v110
	v_mul_f32_e32 v111, v111, v111
	v_mul_f32_e32 v92, v92, v92
	v_mul_f32_e32 v93, v93, v93
	v_mul_f32_e32 v94, v94, v94
	v_mul_f32_e32 v95, v95, v95
	v_mul_f32_e32 v76, v76, v76
	v_mul_f32_e32 v77, v77, v77
	v_mul_f32_e32 v78, v78, v78
	v_mul_f32_e32 v79, v79, v79
	v_cvt_pk_bf16_f32 v124, v124, v125
	v_cvt_pk_bf16_f32 v126, v126, v127
	v_cvt_pk_bf16_f32 v108, v108, v109
	v_cvt_pk_bf16_f32 v110, v110, v111
	v_cvt_pk_bf16_f32 v92, v92, v93
	v_cvt_pk_bf16_f32 v94, v94, v95
	v_cvt_pk_bf16_f32 v76, v76, v77
	v_cvt_pk_bf16_f32 v78, v78, v79
	s_nop 1
	v_permlane16_swap_b32 v124, v126
	v_permlane16_swap_b32 v108, v110
	v_permlane16_swap_b32 v92, v94
	v_permlane16_swap_b32 v76, v78
	s_nop 0
	v_perm_b32 v125, v126, v124, s44
	v_perm_b32 v127, v126, v124, s45
	v_perm_b32 v109, v110, v108, s44
	v_perm_b32 v111, v110, v108, s45
	v_perm_b32 v93, v94, v92, s44
	v_perm_b32 v95, v94, v92, s45
	v_perm_b32 v77, v78, v76, s44
	v_perm_b32 v79, v78, v76, s45
	global_store_dword v164, v125, s[42:43]
	global_store_dword v165, v127, s[42:43]
	global_store_dword v164, v109, s[42:43] offset:64
	global_store_dword v165, v111, s[42:43] offset:64
	global_store_dword v164, v93, s[42:43] offset:128
	global_store_dword v165, v95, s[42:43] offset:128
	global_store_dword v164, v77, s[42:43] offset:192
	global_store_dword v165, v79, s[42:43] offset:192
	v_add_u32_e32 v164, 0x10000, v164
	v_add_u32_e32 v165, 0x10000, v165
	v_mul_f32_e32 v48, v48, v148
	v_mul_f32_e32 v49, v49, v149
	v_mul_f32_e32 v50, v50, v150
	v_mul_f32_e32 v51, v51, v151
	v_mul_f32_e32 v32, v32, v148
	v_mul_f32_e32 v33, v33, v149
	v_mul_f32_e32 v34, v34, v150
	v_mul_f32_e32 v35, v35, v151
	v_mul_f32_e32 v16, v16, v148
	v_mul_f32_e32 v17, v17, v149
	v_mul_f32_e32 v18, v18, v150
	v_mul_f32_e32 v19, v19, v151
	v_mul_f32_e32 v0, v0, v148
	v_mul_f32_e32 v1, v1, v149
	v_mul_f32_e32 v2, v2, v150
	v_mul_f32_e32 v3, v3, v151
	v_max_f32_e32 v48, 0, v48
	v_max_f32_e32 v49, 0, v49
	v_max_f32_e32 v50, 0, v50
	v_max_f32_e32 v51, 0, v51
	v_max_f32_e32 v32, 0, v32
	v_max_f32_e32 v33, 0, v33
	v_max_f32_e32 v34, 0, v34
	v_max_f32_e32 v35, 0, v35
	v_max_f32_e32 v16, 0, v16
	v_max_f32_e32 v17, 0, v17
	v_max_f32_e32 v18, 0, v18
	v_max_f32_e32 v19, 0, v19
	v_max_f32_e32 v0, 0, v0
	v_max_f32_e32 v1, 0, v1
	v_max_f32_e32 v2, 0, v2
	v_max_f32_e32 v3, 0, v3
	v_mul_f32_e32 v48, v48, v48
	v_mul_f32_e32 v49, v49, v49
	v_mul_f32_e32 v50, v50, v50
	v_mul_f32_e32 v51, v51, v51
	v_mul_f32_e32 v32, v32, v32
	v_mul_f32_e32 v33, v33, v33
	v_mul_f32_e32 v34, v34, v34
	v_mul_f32_e32 v35, v35, v35
	v_mul_f32_e32 v16, v16, v16
	v_mul_f32_e32 v17, v17, v17
	v_mul_f32_e32 v18, v18, v18
	v_mul_f32_e32 v19, v19, v19
	v_mul_f32_e32 v0, v0, v0
	v_mul_f32_e32 v1, v1, v1
	v_mul_f32_e32 v2, v2, v2
	v_mul_f32_e32 v3, v3, v3
	v_cvt_pk_bf16_f32 v48, v48, v49
	v_cvt_pk_bf16_f32 v50, v50, v51
	v_cvt_pk_bf16_f32 v32, v32, v33
	v_cvt_pk_bf16_f32 v34, v34, v35
	v_cvt_pk_bf16_f32 v16, v16, v17
	v_cvt_pk_bf16_f32 v18, v18, v19
	v_cvt_pk_bf16_f32 v0, v0, v1
	v_cvt_pk_bf16_f32 v2, v2, v3
	s_nop 1
	v_permlane16_swap_b32 v48, v50
	v_permlane16_swap_b32 v32, v34
	v_permlane16_swap_b32 v16, v18
	v_permlane16_swap_b32 v0, v2
	s_nop 0
	v_perm_b32 v49, v50, v48, s44
	v_perm_b32 v51, v50, v48, s45
	v_perm_b32 v33, v34, v32, s44
	v_perm_b32 v35, v34, v32, s45
	v_perm_b32 v17, v18, v16, s44
	v_perm_b32 v19, v18, v16, s45
	v_perm_b32 v1, v2, v0, s44
	v_perm_b32 v3, v2, v0, s45
	global_store_dword v164, v49, s[42:43]
	global_store_dword v165, v51, s[42:43]
	global_store_dword v164, v33, s[42:43] offset:64
	global_store_dword v165, v35, s[42:43] offset:64
	global_store_dword v164, v17, s[42:43] offset:128
	global_store_dword v165, v19, s[42:43] offset:128
	global_store_dword v164, v1, s[42:43] offset:192
	global_store_dword v165, v3, s[42:43] offset:192
	v_add_u32_e32 v164, 0x10000, v164
	v_add_u32_e32 v165, 0x10000, v165
	v_mul_f32_e32 v52, v52, v152
	v_mul_f32_e32 v53, v53, v153
	v_mul_f32_e32 v54, v54, v154
	v_mul_f32_e32 v55, v55, v155
	v_mul_f32_e32 v36, v36, v152
	v_mul_f32_e32 v37, v37, v153
	v_mul_f32_e32 v38, v38, v154
	v_mul_f32_e32 v39, v39, v155
	v_mul_f32_e32 v20, v20, v152
	v_mul_f32_e32 v21, v21, v153
	v_mul_f32_e32 v22, v22, v154
	v_mul_f32_e32 v23, v23, v155
	v_mul_f32_e32 v4, v4, v152
	v_mul_f32_e32 v5, v5, v153
	v_mul_f32_e32 v6, v6, v154
	v_mul_f32_e32 v7, v7, v155
	v_max_f32_e32 v52, 0, v52
	v_max_f32_e32 v53, 0, v53
	v_max_f32_e32 v54, 0, v54
	v_max_f32_e32 v55, 0, v55
	v_max_f32_e32 v36, 0, v36
	v_max_f32_e32 v37, 0, v37
	v_max_f32_e32 v38, 0, v38
	v_max_f32_e32 v39, 0, v39
	v_max_f32_e32 v20, 0, v20
	v_max_f32_e32 v21, 0, v21
	v_max_f32_e32 v22, 0, v22
	v_max_f32_e32 v23, 0, v23
	v_max_f32_e32 v4, 0, v4
	v_max_f32_e32 v5, 0, v5
	v_max_f32_e32 v6, 0, v6
	v_max_f32_e32 v7, 0, v7
	v_mul_f32_e32 v52, v52, v52
	v_mul_f32_e32 v53, v53, v53
	v_mul_f32_e32 v54, v54, v54
	v_mul_f32_e32 v55, v55, v55
	v_mul_f32_e32 v36, v36, v36
	v_mul_f32_e32 v37, v37, v37
	v_mul_f32_e32 v38, v38, v38
	v_mul_f32_e32 v39, v39, v39
	v_mul_f32_e32 v20, v20, v20
	v_mul_f32_e32 v21, v21, v21
	v_mul_f32_e32 v22, v22, v22
	v_mul_f32_e32 v23, v23, v23
	v_mul_f32_e32 v4, v4, v4
	v_mul_f32_e32 v5, v5, v5
	v_mul_f32_e32 v6, v6, v6
	v_mul_f32_e32 v7, v7, v7
	v_cvt_pk_bf16_f32 v52, v52, v53
	v_cvt_pk_bf16_f32 v54, v54, v55
	v_cvt_pk_bf16_f32 v36, v36, v37
	v_cvt_pk_bf16_f32 v38, v38, v39
	v_cvt_pk_bf16_f32 v20, v20, v21
	v_cvt_pk_bf16_f32 v22, v22, v23
	v_cvt_pk_bf16_f32 v4, v4, v5
	v_cvt_pk_bf16_f32 v6, v6, v7
	s_nop 1
	v_permlane16_swap_b32 v52, v54
	v_permlane16_swap_b32 v36, v38
	v_permlane16_swap_b32 v20, v22
	v_permlane16_swap_b32 v4, v6
	s_nop 0
	v_perm_b32 v53, v54, v52, s44
	v_perm_b32 v55, v54, v52, s45
	v_perm_b32 v37, v38, v36, s44
	v_perm_b32 v39, v38, v36, s45
	v_perm_b32 v21, v22, v20, s44
	v_perm_b32 v23, v22, v20, s45
	v_perm_b32 v5, v6, v4, s44
	v_perm_b32 v7, v6, v4, s45
	global_store_dword v164, v53, s[42:43]
	global_store_dword v165, v55, s[42:43]
	global_store_dword v164, v37, s[42:43] offset:64
	global_store_dword v165, v39, s[42:43] offset:64
	global_store_dword v164, v21, s[42:43] offset:128
	global_store_dword v165, v23, s[42:43] offset:128
	global_store_dword v164, v5, s[42:43] offset:192
	global_store_dword v165, v7, s[42:43] offset:192
	v_add_u32_e32 v164, 0x10000, v164
	v_add_u32_e32 v165, 0x10000, v165
	v_mul_f32_e32 v56, v56, v156
	v_mul_f32_e32 v57, v57, v157
	v_mul_f32_e32 v58, v58, v158
	v_mul_f32_e32 v59, v59, v159
	v_mul_f32_e32 v40, v40, v156
	v_mul_f32_e32 v41, v41, v157
	v_mul_f32_e32 v42, v42, v158
	v_mul_f32_e32 v43, v43, v159
	v_mul_f32_e32 v24, v24, v156
	v_mul_f32_e32 v25, v25, v157
	v_mul_f32_e32 v26, v26, v158
	v_mul_f32_e32 v27, v27, v159
	v_mul_f32_e32 v8, v8, v156
	v_mul_f32_e32 v9, v9, v157
	v_mul_f32_e32 v10, v10, v158
	v_mul_f32_e32 v11, v11, v159
	v_max_f32_e32 v56, 0, v56
	v_max_f32_e32 v57, 0, v57
	v_max_f32_e32 v58, 0, v58
	v_max_f32_e32 v59, 0, v59
	v_max_f32_e32 v40, 0, v40
	v_max_f32_e32 v41, 0, v41
	v_max_f32_e32 v42, 0, v42
	v_max_f32_e32 v43, 0, v43
	v_max_f32_e32 v24, 0, v24
	v_max_f32_e32 v25, 0, v25
	v_max_f32_e32 v26, 0, v26
	v_max_f32_e32 v27, 0, v27
	v_max_f32_e32 v8, 0, v8
	v_max_f32_e32 v9, 0, v9
	v_max_f32_e32 v10, 0, v10
	v_max_f32_e32 v11, 0, v11
	v_mul_f32_e32 v56, v56, v56
	v_mul_f32_e32 v57, v57, v57
	v_mul_f32_e32 v58, v58, v58
	v_mul_f32_e32 v59, v59, v59
	v_mul_f32_e32 v40, v40, v40
	v_mul_f32_e32 v41, v41, v41
	v_mul_f32_e32 v42, v42, v42
	v_mul_f32_e32 v43, v43, v43
	v_mul_f32_e32 v24, v24, v24
	v_mul_f32_e32 v25, v25, v25
	v_mul_f32_e32 v26, v26, v26
	v_mul_f32_e32 v27, v27, v27
	v_mul_f32_e32 v8, v8, v8
	v_mul_f32_e32 v9, v9, v9
	v_mul_f32_e32 v10, v10, v10
	v_mul_f32_e32 v11, v11, v11
	v_cvt_pk_bf16_f32 v56, v56, v57
	v_cvt_pk_bf16_f32 v58, v58, v59
	v_cvt_pk_bf16_f32 v40, v40, v41
	v_cvt_pk_bf16_f32 v42, v42, v43
	v_cvt_pk_bf16_f32 v24, v24, v25
	v_cvt_pk_bf16_f32 v26, v26, v27
	v_cvt_pk_bf16_f32 v8, v8, v9
	v_cvt_pk_bf16_f32 v10, v10, v11
	s_nop 1
	v_permlane16_swap_b32 v56, v58
	v_permlane16_swap_b32 v40, v42
	v_permlane16_swap_b32 v24, v26
	v_permlane16_swap_b32 v8, v10
	s_nop 0
	v_perm_b32 v57, v58, v56, s44
	v_perm_b32 v59, v58, v56, s45
	v_perm_b32 v41, v42, v40, s44
	v_perm_b32 v43, v42, v40, s45
	v_perm_b32 v25, v26, v24, s44
	v_perm_b32 v27, v26, v24, s45
	v_perm_b32 v9, v10, v8, s44
	v_perm_b32 v11, v10, v8, s45
	global_store_dword v164, v57, s[42:43]
	global_store_dword v165, v59, s[42:43]
	global_store_dword v164, v41, s[42:43] offset:64
	global_store_dword v165, v43, s[42:43] offset:64
	global_store_dword v164, v25, s[42:43] offset:128
	global_store_dword v165, v27, s[42:43] offset:128
	global_store_dword v164, v9, s[42:43] offset:192
	global_store_dword v165, v11, s[42:43] offset:192
	v_add_u32_e32 v164, 0x10000, v164
	v_add_u32_e32 v165, 0x10000, v165
	v_mul_f32_e32 v60, v60, v160
	v_mul_f32_e32 v61, v61, v161
	v_mul_f32_e32 v62, v62, v162
	v_mul_f32_e32 v63, v63, v163
	v_mul_f32_e32 v44, v44, v160
	v_mul_f32_e32 v45, v45, v161
	v_mul_f32_e32 v46, v46, v162
	v_mul_f32_e32 v47, v47, v163
	v_mul_f32_e32 v28, v28, v160
	v_mul_f32_e32 v29, v29, v161
	v_mul_f32_e32 v30, v30, v162
	v_mul_f32_e32 v31, v31, v163
	v_mul_f32_e32 v12, v12, v160
	v_mul_f32_e32 v13, v13, v161
	v_mul_f32_e32 v14, v14, v162
	v_mul_f32_e32 v15, v15, v163
	v_max_f32_e32 v60, 0, v60
	v_max_f32_e32 v61, 0, v61
	v_max_f32_e32 v62, 0, v62
	v_max_f32_e32 v63, 0, v63
	v_max_f32_e32 v44, 0, v44
	v_max_f32_e32 v45, 0, v45
	v_max_f32_e32 v46, 0, v46
	v_max_f32_e32 v47, 0, v47
	v_max_f32_e32 v28, 0, v28
	v_max_f32_e32 v29, 0, v29
	v_max_f32_e32 v30, 0, v30
	v_max_f32_e32 v31, 0, v31
	v_max_f32_e32 v12, 0, v12
	v_max_f32_e32 v13, 0, v13
	v_max_f32_e32 v14, 0, v14
	v_max_f32_e32 v15, 0, v15
	v_mul_f32_e32 v60, v60, v60
	v_mul_f32_e32 v61, v61, v61
	v_mul_f32_e32 v62, v62, v62
	v_mul_f32_e32 v63, v63, v63
	v_mul_f32_e32 v44, v44, v44
	v_mul_f32_e32 v45, v45, v45
	v_mul_f32_e32 v46, v46, v46
	v_mul_f32_e32 v47, v47, v47
	v_mul_f32_e32 v28, v28, v28
	v_mul_f32_e32 v29, v29, v29
	v_mul_f32_e32 v30, v30, v30
	v_mul_f32_e32 v31, v31, v31
	v_mul_f32_e32 v12, v12, v12
	v_mul_f32_e32 v13, v13, v13
	v_mul_f32_e32 v14, v14, v14
	v_mul_f32_e32 v15, v15, v15
	v_cvt_pk_bf16_f32 v60, v60, v61
	v_cvt_pk_bf16_f32 v62, v62, v63
	v_cvt_pk_bf16_f32 v44, v44, v45
	v_cvt_pk_bf16_f32 v46, v46, v47
	v_cvt_pk_bf16_f32 v28, v28, v29
	v_cvt_pk_bf16_f32 v30, v30, v31
	v_cvt_pk_bf16_f32 v12, v12, v13
	v_cvt_pk_bf16_f32 v14, v14, v15
	s_nop 1
	v_permlane16_swap_b32 v60, v62
	v_permlane16_swap_b32 v44, v46
	v_permlane16_swap_b32 v28, v30
	v_permlane16_swap_b32 v12, v14
	s_nop 0
	v_perm_b32 v61, v62, v60, s44
	v_perm_b32 v63, v62, v60, s45
	v_perm_b32 v45, v46, v44, s44
	v_perm_b32 v47, v46, v44, s45
	v_perm_b32 v29, v30, v28, s44
	v_perm_b32 v31, v30, v28, s45
	v_perm_b32 v13, v14, v12, s44
	v_perm_b32 v15, v14, v12, s45
	global_store_dword v164, v61, s[42:43]
	global_store_dword v165, v63, s[42:43]
	global_store_dword v164, v45, s[42:43] offset:64
	global_store_dword v165, v47, s[42:43] offset:64
	global_store_dword v164, v29, s[42:43] offset:128
	global_store_dword v165, v31, s[42:43] offset:128
	global_store_dword v164, v13, s[42:43] offset:192
	global_store_dword v165, v15, s[42:43] offset:192
	s_add_i32 s4, s4, s90
	s_cmpk_gt_i32 s4, 0x7ff
	s_barrier
	s_cbranch_scc1 .LBB0_496

.LBB0_488:
	s_or_b64 exec, exec, s[26:27]
	s_lshl_b32 s6, s7, 8
	s_lshl_b64 s[40:41], s[0:1], 11
	s_add_u32 s42, s66, s40
	s_addc_u32 s43, s67, s41
	s_lshl_b32 s7, s7, 19
	s_add_u32 s44, s2, s7
	s_addc_u32 s45, s3, 0
	v_lshrrev_b32_e32 v196, 3, v197
	v_and_b32_e32 v198, 7, v197
	v_lshlrev_b32_e32 v178, 11, v196
	v_lshl_or_b32 v178, v198, 4, v178
	v_add_u32_e32 v179, 0x10000, v178
	v_add_u32_e32 v180, 0x20000, v178
	v_add_u32_e32 v181, 0x30000, v178
	v_and_b32_e32 v176, 15, v196
	v_lshlrev_b32_e32 v176, 1, v176
	v_bfe_u32 v217, v196, 4, 1
	v_or_b32_e32 v176, v176, v217
	v_lshlrev_b32_e32 v176, 11, v176
	v_lshl_or_b32 v176, v198, 4, v176
	v_add_u32_e32 v216, 0x10000, v176
	v_add_u32_e32 v217, 0x20000, v176
	v_add_u32_e32 v218, 0x30000, v176
	v_add_u32_e32 v182, 0x40000, v176
	v_add_u32_e32 v183, 0x50000, v176
	v_add_u32_e32 v184, 0x60000, v176
	v_add_u32_e32 v185, 0x70000, v176
	global_load_dwordx4 v[128:131], v178, s[42:43]
	global_load_dwordx4 v[132:135], v179, s[42:43]
	global_load_dwordx4 v[136:139], v180, s[42:43]
	global_load_dwordx4 v[140:143], v181, s[42:43]
	global_load_dwordx4 v[144:147], v176, s[44:45]
	global_load_dwordx4 v[148:151], v216, s[44:45]
	global_load_dwordx4 v[152:155], v217, s[44:45]
	global_load_dwordx4 v[156:159], v218, s[44:45]
	global_load_dwordx4 v[160:163], v182, s[44:45]
	global_load_dwordx4 v[164:167], v183, s[44:45]
	global_load_dwordx4 v[168:171], v184, s[44:45]
	global_load_dwordx4 v[172:175], v185, s[44:45]
	s_add_u32 s42, s42, 0x80
	s_addc_u32 s43, s43, 0
	s_add_u32 s44, s44, 0x80
	s_addc_u32 s45, s45, 0
	v_bfe_u32 v217, v197, 5, 2
	v_and_b32_e32 v218, 3, v198
	v_xor_b32_e32 v218, v218, v217
	v_lshlrev_b32_e32 v218, 4, v218
	v_lshl_or_b32 v177, v196, 6, v218
	v_lshrrev_b32_e32 v217, 2, v198
	v_lshlrev_b32_e32 v218, 6, v217
	v_xor_b32_e32 v177, v177, v218
	v_mul_u32_u24_e32 v217, 0x6000, v217
	v_add_u32_e32 v177, v177, v217
	v_and_b32_e32 v196, 31, v197
	v_bfe_u32 v198, v197, 5, 1
	v_bfe_u32 v217, v197, 2, 2
	v_xor_b32_e32 v218, v198, v217
	v_xor_b32_e32 v221, 2, v218
	v_lshrrev_b32_e32 v198, 7, v197
	v_lshl_or_b32 v198, v198, 6, v196
	v_lshlrev_b32_e32 v198, 6, v198
	v_lshl_or_b32 v186, v218, 4, v198
	v_lshl_or_b32 v187, v221, 4, v198
	v_bfe_u32 v198, v197, 6, 1
	v_mul_u32_u24_e32 v198, 128, v198
	v_add_u32_e32 v198, v198, v196
	v_lshlrev_b32_e32 v198, 6, v198
	v_add_u32_e32 v198, 0x2000, v198
	v_lshl_or_b32 v188, v218, 4, v198
	v_lshl_or_b32 v189, v221, 4, v198
	v_mov_b64_e32 v[0:1], 0
	v_mov_b64_e32 v[2:3], 0
	v_mov_b64_e32 v[4:5], 0
	v_mov_b64_e32 v[6:7], 0
	v_mov_b64_e32 v[8:9], 0
	v_mov_b64_e32 v[10:11], 0
	v_mov_b64_e32 v[12:13], 0
	v_mov_b64_e32 v[14:15], 0
	v_mov_b64_e32 v[16:17], 0
	v_mov_b64_e32 v[18:19], 0
	v_mov_b64_e32 v[20:21], 0
	v_mov_b64_e32 v[22:23], 0
	v_mov_b64_e32 v[24:25], 0
	v_mov_b64_e32 v[26:27], 0
	v_mov_b64_e32 v[28:29], 0
	v_mov_b64_e32 v[30:31], 0
	v_mov_b64_e32 v[32:33], 0
	v_mov_b64_e32 v[34:35], 0
	v_mov_b64_e32 v[36:37], 0
	v_mov_b64_e32 v[38:39], 0
	v_mov_b64_e32 v[40:41], 0
	v_mov_b64_e32 v[42:43], 0
	v_mov_b64_e32 v[44:45], 0
	v_mov_b64_e32 v[46:47], 0
	v_mov_b64_e32 v[48:49], 0
	v_mov_b64_e32 v[50:51], 0
	v_mov_b64_e32 v[52:53], 0
	v_mov_b64_e32 v[54:55], 0
	v_mov_b64_e32 v[56:57], 0
	v_mov_b64_e32 v[58:59], 0
	v_mov_b64_e32 v[60:61], 0
	v_mov_b64_e32 v[62:63], 0
	v_mov_b64_e32 v[64:65], 0
	v_mov_b64_e32 v[66:67], 0
	v_mov_b64_e32 v[68:69], 0
	v_mov_b64_e32 v[70:71], 0
	v_mov_b64_e32 v[72:73], 0
	v_mov_b64_e32 v[74:75], 0
	v_mov_b64_e32 v[76:77], 0
	v_mov_b64_e32 v[78:79], 0
	v_mov_b64_e32 v[80:81], 0
	v_mov_b64_e32 v[82:83], 0
	v_mov_b64_e32 v[84:85], 0
	v_mov_b64_e32 v[86:87], 0
	v_mov_b64_e32 v[88:89], 0
	v_mov_b64_e32 v[90:91], 0
	v_mov_b64_e32 v[92:93], 0
	v_mov_b64_e32 v[94:95], 0
	v_mov_b64_e32 v[96:97], 0
	v_mov_b64_e32 v[98:99], 0
	v_mov_b64_e32 v[100:101], 0
	v_mov_b64_e32 v[102:103], 0
	v_mov_b64_e32 v[104:105], 0
	v_mov_b64_e32 v[106:107], 0
	v_mov_b64_e32 v[108:109], 0
	v_mov_b64_e32 v[110:111], 0
	v_mov_b64_e32 v[112:113], 0
	v_mov_b64_e32 v[114:115], 0
	v_mov_b64_e32 v[116:117], 0
	v_mov_b64_e32 v[118:119], 0
	v_mov_b64_e32 v[120:121], 0
	v_mov_b64_e32 v[122:123], 0
	v_mov_b64_e32 v[124:125], 0
	v_mov_b64_e32 v[126:127], 0
	s_mov_b32 s36, 0
	s_mov_b32 s37, 0x6000
	s_mov_b32 s1, 0
	s_waitcnt vmcnt(11)
	ds_write_b128 v177, v[128:131]
	s_waitcnt vmcnt(10)
	ds_write_b128 v177, v[132:135] offset:2048
	s_waitcnt vmcnt(9)
	ds_write_b128 v177, v[136:139] offset:4096
	s_waitcnt vmcnt(8)
	ds_write_b128 v177, v[140:143] offset:6144
	s_waitcnt vmcnt(7)
	ds_write_b128 v177, v[144:147] offset:8192
	s_waitcnt vmcnt(6)
	ds_write_b128 v177, v[148:151] offset:10240
	s_waitcnt vmcnt(5)
	ds_write_b128 v177, v[152:155] offset:12288
	s_waitcnt vmcnt(4)
	ds_write_b128 v177, v[156:159] offset:14336
	s_waitcnt vmcnt(3)
	ds_write_b128 v177, v[160:163] offset:16384
	s_waitcnt vmcnt(2)
	ds_write_b128 v177, v[164:167] offset:18432
	s_waitcnt vmcnt(1)
	ds_write_b128 v177, v[168:171] offset:20480
	s_waitcnt vmcnt(0)
	ds_write_b128 v177, v[172:175] offset:22528
	v_subrev_u32_e32 v196, 0x6000, v177
	v_add_u32_e32 v198, 0xc000, v177
	v_min_u32_e32 v177, v196, v198
	v_add_u32_e32 v217, 0x20000, v176
	v_add_u32_e32 v218, 0x30000, v176
	s_waitcnt lgkmcnt(0)
	s_barrier
	s_getreg_b32 s38, hwreg(HW_REG_HW_ID, 0, 4)
	s_bitcmp1_b32 s38, 0
	s_cbranch_scc0 .Lg5_noraise
	s_setprio 1
.Lg5_noraise:
.Lg5_loop:
	v_add_u32_e32 v190, s36, v186
	v_add_u32_e32 v191, s36, v187
	v_add_u32_e32 v250, s36, v188
	v_add_u32_e32 v251, s36, v189
	ds_read_b128 v[200:203], v190
	ds_read_b128 v[204:207], v190 offset:2048
	ds_read_b128 v[222:225], v250
	ds_read_b128 v[226:229], v250 offset:2048
	ds_read_b128 v[230:233], v250 offset:4096
	ds_read_b128 v[234:237], v250 offset:6144
	s_waitcnt lgkmcnt(3)
	v_mfma_f32_32x32x16_bf16 v[112:127], v[200:203], v[222:225], v[112:127]
	global_load_dwordx4 v[128:131], v178, s[42:43]
	ds_read_b128 v[208:211], v191
	v_mfma_f32_32x32x16_bf16 v[48:63], v[204:207], v[222:225], v[48:63]
	global_load_dwordx4 v[132:135], v179, s[42:43]
	ds_read_b128 v[212:215], v191 offset:2048
	s_waitcnt lgkmcnt(4)
	v_mfma_f32_32x32x16_bf16 v[96:111], v[200:203], v[226:229], v[96:111]
	global_load_dwordx4 v[136:139], v180, s[42:43]
	ds_read_b128 v[238:241], v251
	v_mfma_f32_32x32x16_bf16 v[32:47], v[204:207], v[226:229], v[32:47]
	global_load_dwordx4 v[140:143], v181, s[42:43]
	ds_read_b128 v[242:245], v251 offset:2048
	s_waitcnt lgkmcnt(5)
	v_mfma_f32_32x32x16_bf16 v[80:95], v[200:203], v[230:233], v[80:95]
	global_load_dwordx4 v[144:147], v176, s[44:45]
	ds_read_b128 v[246:249], v251 offset:4096
	v_mfma_f32_32x32x16_bf16 v[16:31], v[204:207], v[230:233], v[16:31]
	global_load_dwordx4 v[148:151], v216, s[44:45]
	ds_read_b128 v[192:195], v251 offset:6144
	s_waitcnt lgkmcnt(6)
	v_mfma_f32_32x32x16_bf16 v[64:79], v[200:203], v[234:237], v[64:79]
	global_load_dwordx4 v[152:155], v217, s[44:45]
	v_mfma_f32_32x32x16_bf16 v[0:15], v[204:207], v[234:237], v[0:15]
	global_load_dwordx4 v[156:159], v218, s[44:45]
	v_xad_u32 v190, v186, 64, s37
	v_xad_u32 v250, v188, 64, s37
	s_waitcnt lgkmcnt(3)
	v_mfma_f32_32x32x16_bf16 v[112:127], v[208:211], v[238:241], v[112:127]
	global_load_dwordx4 v[160:163], v182, s[44:45]
	ds_read_b128 v[200:203], v190
	v_mfma_f32_32x32x16_bf16 v[48:63], v[212:215], v[238:241], v[48:63]
	global_load_dwordx4 v[164:167], v183, s[44:45]
	ds_read_b128 v[204:207], v190 offset:2048
	s_waitcnt lgkmcnt(4)
	v_mfma_f32_32x32x16_bf16 v[96:111], v[208:211], v[242:245], v[96:111]
	global_load_dwordx4 v[168:171], v184, s[44:45]
	ds_read_b128 v[222:225], v250
	v_mfma_f32_32x32x16_bf16 v[32:47], v[212:215], v[242:245], v[32:47]
	global_load_dwordx4 v[172:175], v185, s[44:45]
	ds_read_b128 v[226:229], v250 offset:2048
	s_waitcnt lgkmcnt(5)
	v_mfma_f32_32x32x16_bf16 v[80:95], v[208:211], v[246:249], v[80:95]
	ds_read_b128 v[230:233], v250 offset:4096
	v_mfma_f32_32x32x16_bf16 v[16:31], v[212:215], v[246:249], v[16:31]
	ds_read_b128 v[234:237], v250 offset:6144
	s_waitcnt lgkmcnt(6)
	v_mfma_f32_32x32x16_bf16 v[64:79], v[208:211], v[192:195], v[64:79]
	v_mfma_f32_32x32x16_bf16 v[0:15], v[212:215], v[192:195], v[0:15]
	s_barrier
	v_xad_u32 v191, v187, 64, s37
	v_xad_u32 v251, v189, 64, s37
	s_waitcnt lgkmcnt(3)
	v_mfma_f32_32x32x16_bf16 v[112:127], v[200:203], v[222:225], v[112:127]
	ds_read_b128 v[208:211], v191
	v_mfma_f32_32x32x16_bf16 v[48:63], v[204:207], v[222:225], v[48:63]
	ds_read_b128 v[212:215], v191 offset:2048
	s_waitcnt lgkmcnt(4)
	v_mfma_f32_32x32x16_bf16 v[96:111], v[200:203], v[226:229], v[96:111]
	ds_read_b128 v[238:241], v251
	s_waitcnt vmcnt(11)
	ds_write_b128 v177, v[128:131]
	v_mfma_f32_32x32x16_bf16 v[32:47], v[204:207], v[226:229], v[32:47]
	ds_read_b128 v[242:245], v251 offset:2048
	s_waitcnt vmcnt(10)
	ds_write_b128 v177, v[132:135] offset:2048
	s_waitcnt lgkmcnt(7)
	v_mfma_f32_32x32x16_bf16 v[80:95], v[200:203], v[230:233], v[80:95]
	ds_read_b128 v[246:249], v251 offset:4096
	s_waitcnt vmcnt(9)
	ds_write_b128 v177, v[136:139] offset:4096
	v_mfma_f32_32x32x16_bf16 v[16:31], v[204:207], v[230:233], v[16:31]
	ds_read_b128 v[192:195], v251 offset:6144
	s_waitcnt vmcnt(8)
	ds_write_b128 v177, v[140:143] offset:6144
	s_waitcnt lgkmcnt(10)
	v_mfma_f32_32x32x16_bf16 v[64:79], v[200:203], v[234:237], v[64:79]
	s_waitcnt vmcnt(7)
	ds_write_b128 v177, v[144:147] offset:8192
	v_mfma_f32_32x32x16_bf16 v[0:15], v[204:207], v[234:237], v[0:15]
	s_waitcnt vmcnt(6)
	ds_write_b128 v177, v[148:151] offset:10240
	s_waitcnt lgkmcnt(9)
	v_mfma_f32_32x32x16_bf16 v[112:127], v[208:211], v[238:241], v[112:127]
	s_waitcnt vmcnt(5)
	ds_write_b128 v177, v[152:155] offset:12288
	v_mfma_f32_32x32x16_bf16 v[48:63], v[212:215], v[238:241], v[48:63]
	s_waitcnt vmcnt(4)
	ds_write_b128 v177, v[156:159] offset:14336
	s_waitcnt lgkmcnt(9)
	v_mfma_f32_32x32x16_bf16 v[96:111], v[208:211], v[242:245], v[96:111]
	s_waitcnt vmcnt(3)
	ds_write_b128 v177, v[160:163] offset:16384
	v_mfma_f32_32x32x16_bf16 v[32:47], v[212:215], v[242:245], v[32:47]
	s_waitcnt vmcnt(2)
	ds_write_b128 v177, v[164:167] offset:18432
	s_waitcnt lgkmcnt(9)
	v_mfma_f32_32x32x16_bf16 v[80:95], v[208:211], v[246:249], v[80:95]
	s_waitcnt vmcnt(1)
	ds_write_b128 v177, v[168:171] offset:20480
	v_mfma_f32_32x32x16_bf16 v[16:31], v[212:215], v[246:249], v[16:31]
	s_waitcnt vmcnt(0)
	ds_write_b128 v177, v[172:175] offset:22528
	s_waitcnt lgkmcnt(9)
	v_mfma_f32_32x32x16_bf16 v[64:79], v[208:211], v[192:195], v[64:79]
	v_mfma_f32_32x32x16_bf16 v[0:15], v[212:215], v[192:195], v[0:15]
	s_add_u32 s42, s42, 0x80
	s_addc_u32 s43, s43, 0
	s_add_u32 s44, s44, 0x80
	s_addc_u32 s45, s45, 0
	s_sub_i32 s36, s36, 0x6000
	s_cmp_lt_i32 s36, 0
	s_cselect_b32 s38, 0x12000, 0
	s_add_i32 s36, s36, s38
	s_sub_i32 s37, s37, 0x6000
	s_cmp_lt_i32 s37, 0
	s_cselect_b32 s38, 0x12000, 0
	s_add_i32 s37, s37, s38
	v_subrev_u32_e32 v196, 0x6000, v177
	v_add_u32_e32 v198, 0xc000, v177
	v_min_u32_e32 v177, v196, v198
	s_add_i32 s1, s1, 1
	s_cmp_lt_u32 s1, 15
	s_waitcnt lgkmcnt(0)
	s_barrier
	s_cbranch_scc1 .Lg5_loop
	v_add_u32_e32 v190, s36, v186
	v_add_u32_e32 v191, s36, v187
	v_add_u32_e32 v250, s36, v188
	v_add_u32_e32 v251, s36, v189
	ds_read_b128 v[200:203], v190
	ds_read_b128 v[204:207], v190 offset:2048
	ds_read_b128 v[222:225], v250
	ds_read_b128 v[226:229], v250 offset:2048
	ds_read_b128 v[230:233], v250 offset:4096
	ds_read_b128 v[234:237], v250 offset:6144
	s_waitcnt lgkmcnt(3)
	v_mfma_f32_32x32x16_bf16 v[112:127], v[200:203], v[222:225], v[112:127]
	ds_read_b128 v[208:211], v191
	v_mfma_f32_32x32x16_bf16 v[48:63], v[204:207], v[222:225], v[48:63]
	ds_read_b128 v[212:215], v191 offset:2048
	s_waitcnt lgkmcnt(4)
	v_mfma_f32_32x32x16_bf16 v[96:111], v[200:203], v[226:229], v[96:111]
	ds_read_b128 v[238:241], v251
	v_mfma_f32_32x32x16_bf16 v[32:47], v[204:207], v[226:229], v[32:47]
	ds_read_b128 v[242:245], v251 offset:2048
	s_waitcnt lgkmcnt(5)
	v_mfma_f32_32x32x16_bf16 v[80:95], v[200:203], v[230:233], v[80:95]
	ds_read_b128 v[246:249], v251 offset:4096
	v_mfma_f32_32x32x16_bf16 v[16:31], v[204:207], v[230:233], v[16:31]
	ds_read_b128 v[192:195], v251 offset:6144
	s_waitcnt lgkmcnt(6)
	v_mfma_f32_32x32x16_bf16 v[64:79], v[200:203], v[234:237], v[64:79]
	v_mfma_f32_32x32x16_bf16 v[0:15], v[204:207], v[234:237], v[0:15]
	v_xad_u32 v190, v186, 64, s37
	v_xad_u32 v250, v188, 64, s37
	s_waitcnt lgkmcnt(3)
	v_mfma_f32_32x32x16_bf16 v[112:127], v[208:211], v[238:241], v[112:127]
	ds_read_b128 v[200:203], v190
	v_mfma_f32_32x32x16_bf16 v[48:63], v[212:215], v[238:241], v[48:63]
	ds_read_b128 v[204:207], v190 offset:2048
	s_waitcnt lgkmcnt(4)
	v_mfma_f32_32x32x16_bf16 v[96:111], v[208:211], v[242:245], v[96:111]
	ds_read_b128 v[222:225], v250
	v_mfma_f32_32x32x16_bf16 v[32:47], v[212:215], v[242:245], v[32:47]
	ds_read_b128 v[226:229], v250 offset:2048
	s_waitcnt lgkmcnt(5)
	v_mfma_f32_32x32x16_bf16 v[80:95], v[208:211], v[246:249], v[80:95]
	ds_read_b128 v[230:233], v250 offset:4096
	v_mfma_f32_32x32x16_bf16 v[16:31], v[212:215], v[246:249], v[16:31]
	ds_read_b128 v[234:237], v250 offset:6144
	s_waitcnt lgkmcnt(6)
	v_mfma_f32_32x32x16_bf16 v[64:79], v[208:211], v[192:195], v[64:79]
	v_mfma_f32_32x32x16_bf16 v[0:15], v[212:215], v[192:195], v[0:15]
	v_xad_u32 v191, v187, 64, s37
	v_xad_u32 v251, v189, 64, s37
	s_waitcnt lgkmcnt(3)
	v_mfma_f32_32x32x16_bf16 v[112:127], v[200:203], v[222:225], v[112:127]
	ds_read_b128 v[208:211], v191
	v_mfma_f32_32x32x16_bf16 v[48:63], v[204:207], v[222:225], v[48:63]
	ds_read_b128 v[212:215], v191 offset:2048
	s_waitcnt lgkmcnt(4)
	v_mfma_f32_32x32x16_bf16 v[96:111], v[200:203], v[226:229], v[96:111]
	ds_read_b128 v[238:241], v251
	v_mfma_f32_32x32x16_bf16 v[32:47], v[204:207], v[226:229], v[32:47]
	ds_read_b128 v[242:245], v251 offset:2048
	s_waitcnt lgkmcnt(5)
	v_mfma_f32_32x32x16_bf16 v[80:95], v[200:203], v[230:233], v[80:95]
	ds_read_b128 v[246:249], v251 offset:4096
	v_mfma_f32_32x32x16_bf16 v[16:31], v[204:207], v[230:233], v[16:31]
	ds_read_b128 v[192:195], v251 offset:6144
	s_waitcnt lgkmcnt(6)
	v_mfma_f32_32x32x16_bf16 v[64:79], v[200:203], v[234:237], v[64:79]
	v_mfma_f32_32x32x16_bf16 v[0:15], v[204:207], v[234:237], v[0:15]
	s_waitcnt lgkmcnt(3)
	v_mfma_f32_32x32x16_bf16 v[112:127], v[208:211], v[238:241], v[112:127]
	v_mfma_f32_32x32x16_bf16 v[48:63], v[212:215], v[238:241], v[48:63]
	s_waitcnt lgkmcnt(2)
	v_mfma_f32_32x32x16_bf16 v[96:111], v[208:211], v[242:245], v[96:111]
	v_mfma_f32_32x32x16_bf16 v[32:47], v[212:215], v[242:245], v[32:47]
	s_waitcnt lgkmcnt(1)
	v_mfma_f32_32x32x16_bf16 v[80:95], v[208:211], v[246:249], v[80:95]
	v_mfma_f32_32x32x16_bf16 v[16:31], v[212:215], v[246:249], v[16:31]
	s_waitcnt lgkmcnt(0)
	v_mfma_f32_32x32x16_bf16 v[64:79], v[208:211], v[192:195], v[64:79]
	v_mfma_f32_32x32x16_bf16 v[0:15], v[212:215], v[192:195], v[0:15]
	s_setprio 0
	s_nop 7
	s_nop 7
	s_branch .LBB0_482
